# baseline (speedup 1.0000x reference)
; #define MFMA32(a, b, c) __builtin_amdgcn_mfma_f32_32x32x16_bf16((a), (b), (c), 0, 0, 0)
; DI float bflo(unsigned p) { return __uint_as_float(p << 16); }
; DI float bfhi(unsigned p) { return __uint_as_float(p & 0xffff0000u); }
; DI void hgrn_out(const Params& P, int l, int item, char* smem) {
;     ...
;     _Pragma("unroll 2") for (int ks = 0; ks < 8; ++ks) {
;       const int dk0 = 16 * ks + 8 * h;
;       u32x4 qraw = *(const u32x4*)(P.hq + (size_t)(t0 + t) * 1024 + head * 128 + dk0);
;       float4 bt0 = *(const float4*)(bs + t * BST + dk0), bt1 = *(const float4*)(bs + t * BST + dk0 + 4);
;       float4 rf0 = *(const float4*)(bs + 32 * BST + dk0), rf1 = *(const float4*)(bs + 32 * BST + dk0 + 4);
;       float q0 = bflo(qraw[0]), q1 = bfhi(qraw[0]), q2 = bflo(qraw[1]), q3 = bfhi(qraw[1]);
;       float q4 = bflo(qraw[2]), q5 = bfhi(qraw[2]), q6 = bflo(qraw[3]), q7 = bfhi(qraw[3]);
;       bf16x8 qref = pack8(q0 * __expf(bt0.x - rf0.x), q1 * __expf(bt0.y - rf0.y), q2 * __expf(bt0.z - rf0.z), q3 * __expf(bt0.w - rf0.w),
;                           q4 * __expf(bt1.x - rf1.x), q5 * __expf(bt1.y - rf1.y), q6 * __expf(bt1.z - rf1.z), q7 * __expf(bt1.w - rf1.w));
;       bf16x8 qint = pack8(q0 * __expf(bt0.x), q1 * __expf(bt0.y), q2 * __expf(bt0.z), q3 * __expf(bt0.w),
;                           q4 * __expf(bt1.x), q5 * __expf(bt1.y), q6 * __expf(bt1.z), q7 * __expf(bt1.w));
;       _Pragma("unroll") for (int st = 0; st < 2; ++st) {
;         const int s_ = 32 * st + r;
;         u32x4 kraw = *(const u32x4*)(kk + (size_t)(t0 + s_) * 1024 + head * 128 + dk0);
;         float4 b0 = *(const float4*)(bs + s_ * BST + dk0), b1 = *(const float4*)(bs + s_ * BST + dk0 + 4);
;         bf16x8 kt = pack8(bflo(kraw[0]) * __expf(rf0.x - b0.x), bfhi(kraw[0]) * __expf(rf0.y - b0.y),
;                           bflo(kraw[1]) * __expf(rf0.z - b0.z), bfhi(kraw[1]) * __expf(rf0.w - b0.w),
;                           bflo(kraw[2]) * __expf(rf1.x - b1.x), bfhi(kraw[2]) * __expf(rf1.y - b1.y),
;                           bflo(kraw[3]) * __expf(rf1.z - b1.z), bfhi(kraw[3]) * __expf(rf1.w - b1.w));
;         sc[st] = MFMA32(kt, qref, sc[st]);
;       }
.LBB0_743:
	v_lshl_add_u64 v[226:227], v[116:117], 0, s[76:77]
	v_lshl_add_u64 v[230:231], v[122:123], 0, s[76:77]
	v_lshl_add_u64 v[234:235], v[120:121], 0, s[76:77]
	v_lshl_add_u64 v[238:239], v[118:119], 0, s[76:77]
	global_load_dwordx4 v[206:209], v[226:227], off
	global_load_dwordx4 v[210:213], v[230:231], off
	global_load_dwordx4 v[214:217], v[234:235], off
	global_load_dwordx4 v[218:221], v[238:239], off
	v_add_co_u32_e32 v242, vcc, s33, v238
	s_nop 1
	v_addc_co_u32_e32 v243, vcc, 0, v239, vcc
	global_load_dwordx4 v[222:225], v[242:243], off
	global_load_dwordx4 v[226:229], v[226:227], off offset:32
	global_load_dwordx4 v[230:233], v[230:231], off offset:32
	global_load_dwordx4 v[234:237], v[234:235], off offset:32
	global_load_dwordx4 v[238:241], v[238:239], off offset:32
	global_load_dwordx4 v[242:245], v[242:243], off offset:32
	v_lshl_add_u64 v[132:133], v[116:117], 0, s[76:77]
	v_add_u32_e32 v156, v154, v139
	ds_read_b128 v[76:79], v156
	ds_read_b128 v[124:127], v156 offset:16
	ds_read_b128 v[72:75], v154 offset:16896
	ds_read_b128 v[68:71], v154 offset:16912
	s_waitcnt lgkmcnt(1)
	v_sub_f32_e32 v128, v76, v72
	v_sub_f32_e32 v129, v77, v73
	v_sub_f32_e32 v130, v78, v74
	v_sub_f32_e32 v131, v79, v75
	v_mul_f32_e32 v128, 0x3fb8aa3b, v128
	v_mul_f32_e32 v129, 0x3fb8aa3b, v129
	v_mul_f32_e32 v130, 0x3fb8aa3b, v130
	v_mul_f32_e32 v131, 0x3fb8aa3b, v131
	v_exp_f32_e32 v128, v128
	v_exp_f32_e32 v129, v129
	v_exp_f32_e32 v130, v130
	v_exp_f32_e32 v131, v131
	s_waitcnt lgkmcnt(0)
	v_sub_f32_e32 v155, v124, v68
	v_mul_f32_e32 v76, 0x3fb8aa3b, v76
	v_mul_f32_e32 v155, 0x3fb8aa3b, v155
	v_exp_f32_e32 v162, v76
	v_mul_f32_e32 v76, 0x3fb8aa3b, v77
	v_exp_f32_e32 v158, v155
	v_sub_f32_e32 v155, v125, v69
	v_exp_f32_e32 v163, v76
	v_mul_f32_e32 v155, 0x3fb8aa3b, v155
	v_exp_f32_e32 v159, v155
	v_sub_f32_e32 v155, v126, v70
	v_mul_f32_e32 v155, 0x3fb8aa3b, v155
	v_exp_f32_e32 v160, v155
	v_sub_f32_e32 v155, v127, v71
	v_mul_f32_e32 v155, 0x3fb8aa3b, v155
	v_exp_f32_e32 v161, v155
	v_add_u32_e32 v155, v154, v142
	s_waitcnt vmcnt(9)
	v_lshlrev_b32_e32 v164, 16, v206
	v_and_b32_e32 v165, 0xffff0000, v206
	v_mul_f32_e32 v64, 0x3fb8aa3b, v78
	v_exp_f32_e32 v78, v64
	v_mul_f32_e32 v64, 0x3fb8aa3b, v79
	v_exp_f32_e32 v79, v64
	v_lshlrev_b32_e32 v64, 16, v207
	v_and_b32_e32 v65, 0xffff0000, v207
	v_mul_f32_e32 v76, v128, v164
	v_mul_f32_e32 v77, v129, v165
	v_mul_f32_e32 v130, v130, v64
	v_mul_f32_e32 v131, v131, v65
	v_cvt_pk_bf16_f32 v76, v76, v77
	v_cvt_pk_bf16_f32 v77, v130, v131
	v_mul_f32_e32 v130, v78, v64
	v_mul_f32_e32 v131, v79, v65
	v_mul_f32_e32 v64, 0x3fb8aa3b, v124
	v_mul_f32_e32 v65, 0x3fb8aa3b, v125
	v_exp_f32_e32 v64, v64
	v_exp_f32_e32 v65, v65
	v_lshlrev_b32_e32 v124, 16, v208
	v_and_b32_e32 v125, 0xffff0000, v208
	v_mul_f32_e32 v78, v158, v124
	v_mul_f32_e32 v79, v159, v125
	v_mul_f32_e32 v124, v64, v124
	v_mul_f32_e32 v125, v65, v125
	v_mul_f32_e32 v64, 0x3fb8aa3b, v126
	v_mul_f32_e32 v65, 0x3fb8aa3b, v127
	v_exp_f32_e32 v64, v64
	v_exp_f32_e32 v65, v65
	v_lshlrev_b32_e32 v66, 16, v209
	v_and_b32_e32 v67, 0xffff0000, v209
	v_mul_f32_e32 v126, v160, v66
	v_mul_f32_e32 v127, v161, v67
	v_mul_f32_e32 v128, v162, v164
	v_mul_f32_e32 v129, v163, v165
	v_cvt_pk_bf16_f32 v78, v78, v79
	v_cvt_pk_bf16_f32 v79, v126, v127
	v_mul_f32_e32 v126, v64, v66
	v_mul_f32_e32 v127, v65, v67
	v_cvt_pk_bf16_f32 v66, v124, v125
	v_lshl_add_u64 v[124:125], v[122:123], 0, s[76:77]
	v_cvt_pk_bf16_f32 v64, v128, v129
	v_cvt_pk_bf16_f32 v67, v126, v127
	ds_read_b128 v[158:161], v155
	ds_read_b128 v[162:165], v155 offset:16
	v_cvt_pk_bf16_f32 v65, v130, v131
	s_waitcnt lgkmcnt(1)
	v_sub_f32_e32 v130, v72, v158
	v_sub_f32_e32 v131, v73, v159
	v_mul_f32_e32 v130, 0x3fb8aa3b, v130
	v_mul_f32_e32 v131, 0x3fb8aa3b, v131
	v_exp_f32_e32 v130, v130
	v_exp_f32_e32 v131, v131
	s_waitcnt vmcnt(8)
	v_lshlrev_b32_e32 v158, 16, v210
	v_and_b32_e32 v159, 0xffff0000, v210
	v_sub_f32_e32 v126, v74, v160
	v_mul_f32_e32 v126, 0x3fb8aa3b, v126
	v_mul_f32_e32 v130, v130, v158
	v_mul_f32_e32 v131, v131, v159
	v_exp_f32_e32 v158, v126
	v_sub_f32_e32 v126, v75, v161
	v_mul_f32_e32 v126, 0x3fb8aa3b, v126
	v_exp_f32_e32 v159, v126
	v_lshlrev_b32_e32 v126, 16, v211
	v_and_b32_e32 v127, 0xffff0000, v211
	v_lshlrev_b32_e32 v160, 16, v212
	v_mul_f32_e32 v158, v158, v126
	v_mul_f32_e32 v159, v159, v127
	s_waitcnt lgkmcnt(0)
	v_sub_f32_e32 v126, v68, v162
	v_sub_f32_e32 v127, v69, v163
	v_mul_f32_e32 v126, 0x3fb8aa3b, v126
	v_mul_f32_e32 v127, 0x3fb8aa3b, v127
	v_exp_f32_e32 v126, v126
	v_exp_f32_e32 v127, v127
	v_and_b32_e32 v161, 0xffff0000, v212
	v_lshlrev_b32_e32 v128, 16, v213
	v_and_b32_e32 v129, 0xffff0000, v213
	v_mul_f32_e32 v160, v126, v160
	v_mul_f32_e32 v161, v127, v161
	v_sub_f32_e32 v126, v70, v164
	v_sub_f32_e32 v127, v71, v165
	v_mul_f32_e32 v126, 0x3fb8aa3b, v126
	v_mul_f32_e32 v127, 0x3fb8aa3b, v127
	v_exp_f32_e32 v126, v126
	v_exp_f32_e32 v127, v127
	s_nop 0
	v_mul_f32_e32 v162, v126, v128
	v_mul_f32_e32 v163, v127, v129
	v_cvt_pk_bf16_f32 v126, v130, v131
	v_cvt_pk_bf16_f32 v127, v158, v159
	v_cvt_pk_bf16_f32 v128, v160, v161
	v_cvt_pk_bf16_f32 v129, v162, v163
	s_nop 1
	v_mfma_f32_32x32x16_bf16 v[48:63], v[126:129], v[76:79], v[48:63]
	v_lshl_add_u64 v[126:127], v[120:121], 0, s[76:77]
	ds_read_b128 v[158:161], v155 offset:16896
	ds_read_b128 v[162:165], v155 offset:16912
	s_waitcnt lgkmcnt(1)
	v_sub_f32_e32 v74, v74, v160
	v_sub_f32_e32 v75, v75, v161
	v_mul_f32_e32 v74, 0x3fb8aa3b, v74
	v_mul_f32_e32 v75, 0x3fb8aa3b, v75
	s_waitcnt lgkmcnt(0)
; #define MFMA32(a, b, c) __builtin_amdgcn_mfma_f32_32x32x16_bf16((a), (b), (c), 0, 0, 0)
; DI float bflo(unsigned p) { return __uint_as_float(p << 16); }
; DI float bfhi(unsigned p) { return __uint_as_float(p & 0xffff0000u); }
; DI void hgrn_out(const Params& P, int l, int item, char* smem) {
;     ...
;     _Pragma("unroll 2") for (int ks = 0; ks < 8; ++ks) {
;       const int dk0 = 16 * ks + 8 * h;
;       u32x4 qraw = *(const u32x4*)(P.hq + (size_t)(t0 + t) * 1024 + head * 128 + dk0);
;       float4 bt0 = *(const float4*)(bs + t * BST + dk0), bt1 = *(const float4*)(bs + t * BST + dk0 + 4);
;       float4 rf0 = *(const float4*)(bs + 32 * BST + dk0), rf1 = *(const float4*)(bs + 32 * BST + dk0 + 4);
;       float q0 = bflo(qraw[0]), q1 = bfhi(qraw[0]), q2 = bflo(qraw[1]), q3 = bfhi(qraw[1]);
;       float q4 = bflo(qraw[2]), q5 = bfhi(qraw[2]), q6 = bflo(qraw[3]), q7 = bfhi(qraw[3]);
;       bf16x8 qref = pack8(q0 * __expf(bt0.x - rf0.x), q1 * __expf(bt0.y - rf0.y), q2 * __expf(bt0.z - rf0.z), q3 * __expf(bt0.w - rf0.w),
;                           q4 * __expf(bt1.x - rf1.x), q5 * __expf(bt1.y - rf1.y), q6 * __expf(bt1.z - rf1.z), q7 * __expf(bt1.w - rf1.w));
;       bf16x8 qint = pack8(q0 * __expf(bt0.x), q1 * __expf(bt0.y), q2 * __expf(bt0.z), q3 * __expf(bt0.w),
;                           q4 * __expf(bt1.x), q5 * __expf(bt1.y), q6 * __expf(bt1.z), q7 * __expf(bt1.w));
;       _Pragma("unroll") for (int st = 0; st < 2; ++st) {
;         const int s_ = 32 * st + r;
;         u32x4 kraw = *(const u32x4*)(kk + (size_t)(t0 + s_) * 1024 + head * 128 + dk0);
;         float4 b0 = *(const float4*)(bs + s_ * BST + dk0), b1 = *(const float4*)(bs + s_ * BST + dk0 + 4);
;         bf16x8 kt = pack8(bflo(kraw[0]) * __expf(rf0.x - b0.x), bfhi(kraw[0]) * __expf(rf0.y - b0.y),
;                           bflo(kraw[1]) * __expf(rf0.z - b0.z), bfhi(kraw[1]) * __expf(rf0.w - b0.w),
;                           bflo(kraw[2]) * __expf(rf1.x - b1.x), bfhi(kraw[2]) * __expf(rf1.y - b1.y),
;                           bflo(kraw[3]) * __expf(rf1.z - b1.z), bfhi(kraw[3]) * __expf(rf1.w - b1.w));
;         sc[st] = MFMA32(kt, qref, sc[st]);
;       }
;       _Pragma("unroll") for (int mi = 0; mi < 2; ++mi) {
;         const int dv = 32 * (2 * dh + mi) + r;
;         bf16x8 sfr = *(const bf16x8*)(stp + dv * 128 + dk0);
;         o[mi] = MFMA32(sfr, qint, o[mi]);
;       }
	v_sub_f32_e32 v68, v68, v162
	v_sub_f32_e32 v69, v69, v163
	v_exp_f32_e32 v74, v74
	v_exp_f32_e32 v75, v75
	v_mul_f32_e32 v68, 0x3fb8aa3b, v68
	v_mul_f32_e32 v69, 0x3fb8aa3b, v69
	v_exp_f32_e32 v68, v68
	v_exp_f32_e32 v69, v69
	v_sub_f32_e32 v72, v72, v158
	v_sub_f32_e32 v73, v73, v159
	v_mul_f32_e32 v72, 0x3fb8aa3b, v72
	v_mul_f32_e32 v73, 0x3fb8aa3b, v73
	v_exp_f32_e32 v72, v72
	v_exp_f32_e32 v73, v73
	s_waitcnt vmcnt(7)
	v_lshlrev_b32_e32 v158, 16, v214
	v_and_b32_e32 v159, 0xffff0000, v214
	v_lshlrev_b32_e32 v128, 16, v215
	v_and_b32_e32 v129, 0xffff0000, v215
	v_mul_f32_e32 v74, v74, v128
	v_mul_f32_e32 v75, v75, v129
	v_lshlrev_b32_e32 v128, 16, v216
	v_and_b32_e32 v129, 0xffff0000, v216
	v_mul_f32_e32 v128, v68, v128
	v_mul_f32_e32 v129, v69, v129
	v_sub_f32_e32 v68, v70, v164
	v_sub_f32_e32 v69, v71, v165
	v_mul_f32_e32 v68, 0x3fb8aa3b, v68
	v_mul_f32_e32 v69, 0x3fb8aa3b, v69
	v_exp_f32_e32 v68, v68
	v_exp_f32_e32 v69, v69
	v_lshlrev_b32_e32 v70, 16, v217
	v_and_b32_e32 v71, 0xffff0000, v217
	v_mul_f32_e32 v72, v72, v158
	v_mul_f32_e32 v73, v73, v159
	v_mul_f32_e32 v130, v68, v70
	v_mul_f32_e32 v131, v69, v71
	v_cvt_pk_bf16_f32 v68, v72, v73
	v_cvt_pk_bf16_f32 v69, v74, v75
	v_cvt_pk_bf16_f32 v70, v128, v129
	v_cvt_pk_bf16_f32 v71, v130, v131
	v_lshl_add_u64 v[130:131], v[118:119], 0, s[76:77]
	v_add_co_u32_e32 v128, vcc, s33, v130
	v_mfma_f32_32x32x16_bf16 v[32:47], v[68:71], v[76:79], v[32:47]
	v_addc_co_u32_e32 v129, vcc, 0, v131, vcc
	s_add_u32 s76, s76, 64
	s_addc_u32 s77, s77, 0
	s_cmpk_eq_i32 s76, 0x100
	s_waitcnt vmcnt(6)
	v_mfma_f32_32x32x16_bf16 v[16:31], v[218:221], v[64:67], v[16:31]
	s_waitcnt vmcnt(5)
	v_mfma_f32_32x32x16_bf16 v[0:15], v[222:225], v[64:67], v[0:15]
	ds_read_b128 v[76:79], v156 offset:64
	ds_read_b128 v[156:159], v156 offset:80
	ds_read_b128 v[72:75], v154 offset:16960
	ds_read_b128 v[68:71], v154 offset:16976
	v_add_u32_e32 v154, 0x80, v154
	s_waitcnt lgkmcnt(1)
	v_sub_f32_e32 v132, v76, v72
	v_sub_f32_e32 v133, v77, v73
	v_sub_f32_e32 v160, v78, v74
	v_sub_f32_e32 v161, v79, v75
	v_mul_f32_e32 v132, 0x3fb8aa3b, v132
	v_mul_f32_e32 v133, 0x3fb8aa3b, v133
	v_mul_f32_e32 v160, 0x3fb8aa3b, v160
	v_mul_f32_e32 v161, 0x3fb8aa3b, v161
	v_exp_f32_e32 v132, v132
	v_exp_f32_e32 v133, v133
	v_exp_f32_e32 v160, v160
	v_exp_f32_e32 v161, v161
	v_mul_f32_e32 v76, 0x3fb8aa3b, v76
	v_exp_f32_e32 v166, v76
	v_mul_f32_e32 v76, 0x3fb8aa3b, v77
	s_waitcnt lgkmcnt(0)
	v_sub_f32_e32 v162, v156, v68
	v_sub_f32_e32 v163, v157, v69
	v_exp_f32_e32 v167, v76
	v_mul_f32_e32 v162, 0x3fb8aa3b, v162
	v_mul_f32_e32 v163, 0x3fb8aa3b, v163
	v_exp_f32_e32 v162, v162
	v_exp_f32_e32 v163, v163
	v_sub_f32_e32 v164, v158, v70
	v_sub_f32_e32 v165, v159, v71
	v_mul_f32_e32 v164, 0x3fb8aa3b, v164
	v_mul_f32_e32 v165, 0x3fb8aa3b, v165
	v_exp_f32_e32 v164, v164
	v_exp_f32_e32 v165, v165
	s_waitcnt vmcnt(4)
	v_lshlrev_b32_e32 v168, 16, v226
	v_and_b32_e32 v169, 0xffff0000, v226
	v_mul_f32_e32 v64, 0x3fb8aa3b, v78
	v_exp_f32_e32 v78, v64
	v_mul_f32_e32 v64, 0x3fb8aa3b, v79
	v_exp_f32_e32 v79, v64
	v_lshlrev_b32_e32 v64, 16, v227
	v_and_b32_e32 v65, 0xffff0000, v227
	v_mul_f32_e32 v76, v132, v168
	v_mul_f32_e32 v77, v133, v169
	v_mul_f32_e32 v160, v160, v64
	v_mul_f32_e32 v161, v161, v65
	v_cvt_pk_bf16_f32 v76, v76, v77
	v_cvt_pk_bf16_f32 v77, v160, v161
	v_mul_f32_e32 v160, v78, v64
	v_mul_f32_e32 v161, v79, v65
	v_mul_f32_e32 v64, 0x3fb8aa3b, v156
	v_mul_f32_e32 v65, 0x3fb8aa3b, v157
	v_exp_f32_e32 v64, v64
	v_exp_f32_e32 v65, v65
	v_lshlrev_b32_e32 v156, 16, v228
	v_and_b32_e32 v157, 0xffff0000, v228
	v_mul_f32_e32 v78, v162, v156
	v_mul_f32_e32 v79, v163, v157
	v_mul_f32_e32 v156, v64, v156
	v_mul_f32_e32 v157, v65, v157
	v_mul_f32_e32 v64, 0x3fb8aa3b, v158
	v_mul_f32_e32 v65, 0x3fb8aa3b, v159
	v_exp_f32_e32 v64, v64
	v_exp_f32_e32 v65, v65
	v_lshlrev_b32_e32 v66, 16, v229
	v_and_b32_e32 v67, 0xffff0000, v229
	v_mul_f32_e32 v158, v164, v66
	v_mul_f32_e32 v159, v165, v67
	v_cvt_pk_bf16_f32 v78, v78, v79
	v_cvt_pk_bf16_f32 v79, v158, v159
	v_mul_f32_e32 v158, v64, v66
	v_mul_f32_e32 v159, v65, v67
	v_cvt_pk_bf16_f32 v66, v156, v157
	v_cvt_pk_bf16_f32 v67, v158, v159
	v_mul_f32_e32 v132, v166, v168
	v_mul_f32_e32 v133, v167, v169
	v_cvt_pk_bf16_f32 v65, v160, v161
	ds_read_b128 v[160:163], v155 offset:64
	ds_read_b128 v[164:167], v155 offset:80
	v_cvt_pk_bf16_f32 v64, v132, v133
	s_waitcnt lgkmcnt(1)
	v_sub_f32_e32 v124, v72, v160
	v_sub_f32_e32 v125, v73, v161
	v_mul_f32_e32 v124, 0x3fb8aa3b, v124
	v_mul_f32_e32 v125, 0x3fb8aa3b, v125
	v_exp_f32_e32 v124, v124
	v_exp_f32_e32 v125, v125
	s_waitcnt vmcnt(3)
	v_lshlrev_b32_e32 v132, 16, v230
	v_and_b32_e32 v133, 0xffff0000, v230
	v_mul_f32_e32 v124, v124, v132
	v_mul_f32_e32 v125, v125, v133
	v_sub_f32_e32 v132, v74, v162
	v_sub_f32_e32 v133, v75, v163
	v_mul_f32_e32 v132, 0x3fb8aa3b, v132
	v_mul_f32_e32 v133, 0x3fb8aa3b, v133
	v_exp_f32_e32 v132, v132
	v_exp_f32_e32 v133, v133
	v_lshlrev_b32_e32 v156, 16, v231
	v_and_b32_e32 v157, 0xffff0000, v231
	v_lshlrev_b32_e32 v160, 16, v232
	v_mul_f32_e32 v132, v132, v156
	v_mul_f32_e32 v133, v133, v157
	s_waitcnt lgkmcnt(0)
	v_sub_f32_e32 v156, v68, v164
	v_sub_f32_e32 v157, v69, v165
	v_mul_f32_e32 v156, 0x3fb8aa3b, v156
	v_mul_f32_e32 v157, 0x3fb8aa3b, v157
	v_exp_f32_e32 v156, v156
	v_exp_f32_e32 v157, v157
	v_and_b32_e32 v161, 0xffff0000, v232
	v_lshlrev_b32_e32 v158, 16, v233
	v_and_b32_e32 v159, 0xffff0000, v233
	v_mul_f32_e32 v160, v156, v160
	v_mul_f32_e32 v161, v157, v161
	v_sub_f32_e32 v156, v70, v166
	v_sub_f32_e32 v157, v71, v167
	v_mul_f32_e32 v156, 0x3fb8aa3b, v156
	v_mul_f32_e32 v157, 0x3fb8aa3b, v157
	v_exp_f32_e32 v156, v156
	v_exp_f32_e32 v157, v157
	s_nop 0
	v_mul_f32_e32 v162, v156, v158
	v_mul_f32_e32 v163, v157, v159
	v_cvt_pk_bf16_f32 v156, v124, v125
	v_cvt_pk_bf16_f32 v157, v132, v133
	v_cvt_pk_bf16_f32 v158, v160, v161
	v_cvt_pk_bf16_f32 v159, v162, v163
	s_waitcnt vmcnt(2)
; #define MFMA32(a, b, c) __builtin_amdgcn_mfma_f32_32x32x16_bf16((a), (b), (c), 0, 0, 0)
; DI float bflo(unsigned p) { return __uint_as_float(p << 16); }
; DI float bfhi(unsigned p) { return __uint_as_float(p & 0xffff0000u); }
; DI int crow(int i, int h) { return (i & 3) + 8 * (i >> 2) + 4 * h; }
; DI void hgrn_out(const Params& P, int l, int item, char* smem) {
;     ...
;                           bflo(kraw[3]) * __expf(rf1.z - b1.z), bfhi(kraw[3]) * __expf(rf1.w - b1.w));
;         sc[st] = MFMA32(kt, qref, sc[st]);
;       }
;       _Pragma("unroll") for (int mi = 0; mi < 2; ++mi) {
;         const int dv = 32 * (2 * dh + mi) + r;
;         bf16x8 sfr = *(const bf16x8*)(stp + dv * 128 + dk0);
;         o[mi] = MFMA32(sfr, qint, o[mi]);
;       }
;     }
;     _Pragma("unroll") for (int st = 0; st < 2; ++st) {
;       _Pragma("unroll") for (int i = 0; i < 16; ++i) {
;         const int s_ = 32 * st + crow(i, h);
;         const bool ok = dir ? (s_ >= t) : (s_ <= t);
;         sc[st][i] = ok ? sc[st][i] : 0.f;
;       }
;     }
	v_lshlrev_b32_e32 v132, 16, v234
	v_mfma_f32_32x32x16_bf16 v[48:63], v[156:159], v[76:79], v[48:63]
	ds_read_b128 v[156:159], v155 offset:16960
	ds_read_b128 v[160:163], v155 offset:16976
	v_and_b32_e32 v133, 0xffff0000, v234
	v_lshlrev_b32_e32 v124, 16, v235
	v_and_b32_e32 v125, 0xffff0000, v235
	s_waitcnt lgkmcnt(1)
	v_sub_f32_e32 v74, v74, v158
	v_sub_f32_e32 v75, v75, v159
	v_mul_f32_e32 v74, 0x3fb8aa3b, v74
	v_mul_f32_e32 v75, 0x3fb8aa3b, v75
	s_waitcnt lgkmcnt(0)
	v_sub_f32_e32 v68, v68, v160
	v_sub_f32_e32 v69, v69, v161
	v_exp_f32_e32 v74, v74
	v_exp_f32_e32 v75, v75
	v_mul_f32_e32 v68, 0x3fb8aa3b, v68
	v_mul_f32_e32 v69, 0x3fb8aa3b, v69
	v_exp_f32_e32 v68, v68
	v_exp_f32_e32 v69, v69
	v_mul_f32_e32 v74, v74, v124
	v_mul_f32_e32 v75, v75, v125
	v_lshlrev_b32_e32 v124, 16, v236
	v_and_b32_e32 v125, 0xffff0000, v236
	v_sub_f32_e32 v72, v72, v156
	v_sub_f32_e32 v73, v73, v157
	v_mul_f32_e32 v124, v68, v124
	v_mul_f32_e32 v125, v69, v125
	v_sub_f32_e32 v68, v70, v162
	v_sub_f32_e32 v69, v71, v163
	v_mul_f32_e32 v72, 0x3fb8aa3b, v72
	v_mul_f32_e32 v73, 0x3fb8aa3b, v73
	v_mul_f32_e32 v68, 0x3fb8aa3b, v68
	v_mul_f32_e32 v69, 0x3fb8aa3b, v69
	v_exp_f32_e32 v72, v72
	v_exp_f32_e32 v73, v73
	v_exp_f32_e32 v68, v68
	v_exp_f32_e32 v69, v69
	v_lshlrev_b32_e32 v70, 16, v237
	v_and_b32_e32 v71, 0xffff0000, v237
	v_mul_f32_e32 v72, v72, v132
	v_mul_f32_e32 v73, v73, v133
	v_mul_f32_e32 v126, v68, v70
	v_mul_f32_e32 v127, v69, v71
	v_cvt_pk_bf16_f32 v68, v72, v73
	v_cvt_pk_bf16_f32 v69, v74, v75
	v_cvt_pk_bf16_f32 v70, v124, v125
	v_cvt_pk_bf16_f32 v71, v126, v127
	s_nop 1
	v_mfma_f32_32x32x16_bf16 v[32:47], v[68:71], v[76:79], v[32:47]
	s_waitcnt vmcnt(1)
	v_mfma_f32_32x32x16_bf16 v[16:31], v[238:241], v[64:67], v[16:31]
	s_waitcnt vmcnt(0)
	v_mfma_f32_32x32x16_bf16 v[0:15], v[242:245], v[64:67], v[0:15]
	s_cbranch_scc0 .LBB0_743
	v_readlane_b32 s4, v247, 16
	v_readlane_b32 s5, v247, 17
	s_mov_b32 s76, 1
	s_nop 0
	v_cndmask_b32_e64 v64, 0, 1, s[4:5]
	v_readlane_b32 s4, v249, 34
	v_readlane_b32 s5, v249, 35
	s_nop 1
	v_cndmask_b32_e64 v65, 0, 1, s[4:5]
	v_cndmask_b32_e64 v64, v65, v64, s[74:75]
	v_readlane_b32 s4, v247, 20
	v_and_b32_e32 v64, 1, v64
	v_readlane_b32 s5, v247, 21
	v_cmp_eq_u32_e32 vcc, 1, v64
	s_nop 0
	v_cndmask_b32_e64 v64, 0, 1, s[4:5]
	v_readlane_b32 s4, v247, 18
	v_readlane_b32 s5, v247, 19
	v_cndmask_b32_e32 v48, 0, v48, vcc
	s_nop 0
	v_cndmask_b32_e64 v65, 0, 1, s[4:5]
	v_cndmask_b32_e64 v64, v65, v64, s[74:75]
	v_readlane_b32 s4, v247, 24
	v_and_b32_e32 v64, 1, v64
	v_readlane_b32 s5, v247, 25
	v_cmp_eq_u32_e32 vcc, 1, v64
	s_nop 0
	v_cndmask_b32_e64 v64, 0, 1, s[4:5]
	v_readlane_b32 s4, v247, 22
	v_readlane_b32 s5, v247, 23
	v_cndmask_b32_e32 v49, 0, v49, vcc
	s_nop 0
	v_cndmask_b32_e64 v65, 0, 1, s[4:5]
	v_cndmask_b32_e64 v64, v65, v64, s[74:75]
	v_readlane_b32 s4, v247, 28
	v_and_b32_e32 v64, 1, v64
	v_readlane_b32 s5, v247, 29
	v_cmp_eq_u32_e32 vcc, 1, v64
	s_nop 0
	v_cndmask_b32_e64 v64, 0, 1, s[4:5]
	v_readlane_b32 s4, v247, 26
	v_readlane_b32 s5, v247, 27
	v_cndmask_b32_e32 v50, 0, v50, vcc
	s_nop 0
	v_cndmask_b32_e64 v65, 0, 1, s[4:5]
	v_cndmask_b32_e64 v64, v65, v64, s[74:75]
	v_readlane_b32 s4, v247, 32
	v_and_b32_e32 v64, 1, v64
	v_readlane_b32 s5, v247, 33
	v_cmp_eq_u32_e32 vcc, 1, v64
	s_nop 0
	v_cndmask_b32_e64 v64, 0, 1, s[4:5]
	v_readlane_b32 s4, v247, 30
	v_readlane_b32 s5, v247, 31
	v_cndmask_b32_e32 v51, 0, v51, vcc
	s_nop 0
	v_cndmask_b32_e64 v65, 0, 1, s[4:5]
	v_cndmask_b32_e64 v64, v65, v64, s[74:75]
	v_readlane_b32 s4, v247, 36
	v_and_b32_e32 v64, 1, v64
	v_readlane_b32 s5, v247, 37
	v_cmp_eq_u32_e32 vcc, 1, v64
	s_nop 0
	v_cndmask_b32_e64 v64, 0, 1, s[4:5]
	v_readlane_b32 s4, v247, 34
	v_readlane_b32 s5, v247, 35
	v_cndmask_b32_e32 v52, 0, v52, vcc
	s_nop 0
	v_cndmask_b32_e64 v65, 0, 1, s[4:5]
	v_cndmask_b32_e64 v64, v65, v64, s[74:75]
	v_readlane_b32 s4, v247, 40
	v_and_b32_e32 v64, 1, v64
	v_readlane_b32 s5, v247, 41
	v_cmp_eq_u32_e32 vcc, 1, v64
	s_nop 0
	v_cndmask_b32_e64 v64, 0, 1, s[4:5]
	v_readlane_b32 s4, v247, 38
	v_readlane_b32 s5, v247, 39
	v_cndmask_b32_e32 v53, 0, v53, vcc
	s_nop 0
	v_cndmask_b32_e64 v65, 0, 1, s[4:5]
	v_cndmask_b32_e64 v64, v65, v64, s[74:75]
	v_readlane_b32 s4, v247, 44
	v_and_b32_e32 v64, 1, v64
	v_readlane_b32 s5, v247, 45
	v_cmp_eq_u32_e32 vcc, 1, v64
	s_nop 0
	v_cndmask_b32_e64 v64, 0, 1, s[4:5]
	v_readlane_b32 s4, v247, 42
	v_readlane_b32 s5, v247, 43
	v_cndmask_b32_e32 v54, 0, v54, vcc
	s_nop 0
	v_cndmask_b32_e64 v65, 0, 1, s[4:5]
	v_cndmask_b32_e64 v64, v65, v64, s[74:75]
	v_readlane_b32 s4, v247, 48
	v_and_b32_e32 v64, 1, v64
	v_readlane_b32 s5, v247, 49
	v_cmp_eq_u32_e32 vcc, 1, v64
	s_nop 0
	v_cndmask_b32_e64 v64, 0, 1, s[4:5]
	v_readlane_b32 s4, v247, 46
	v_readlane_b32 s5, v247, 47
	v_cndmask_b32_e32 v55, 0, v55, vcc
	s_nop 0
	v_cndmask_b32_e64 v65, 0, 1, s[4:5]
	v_cndmask_b32_e64 v64, v65, v64, s[74:75]
	v_readlane_b32 s4, v247, 52
	v_and_b32_e32 v64, 1, v64
	v_readlane_b32 s5, v247, 53
	v_cmp_eq_u32_e32 vcc, 1, v64
	s_nop 0
	v_cndmask_b32_e64 v64, 0, 1, s[4:5]
	v_readlane_b32 s4, v247, 50
	v_readlane_b32 s5, v247, 51
	v_cndmask_b32_e32 v56, 0, v56, vcc
	s_nop 0
	v_cndmask_b32_e64 v65, 0, 1, s[4:5]
	v_cndmask_b32_e64 v64, v65, v64, s[74:75]
	v_readlane_b32 s4, v247, 56
	v_and_b32_e32 v64, 1, v64
	v_readlane_b32 s5, v247, 57
	v_cmp_eq_u32_e32 vcc, 1, v64
	s_nop 0
	v_cndmask_b32_e64 v64, 0, 1, s[4:5]
	v_readlane_b32 s4, v247, 54
	v_readlane_b32 s5, v247, 55
	v_cndmask_b32_e32 v57, 0, v57, vcc
	s_nop 0
	v_cndmask_b32_e64 v65, 0, 1, s[4:5]
	v_cndmask_b32_e64 v64, v65, v64, s[74:75]
	v_readlane_b32 s4, v247, 60
	v_and_b32_e32 v64, 1, v64
	v_readlane_b32 s5, v247, 61
; #define MFMA32(a, b, c) __builtin_amdgcn_mfma_f32_32x32x16_bf16((a), (b), (c), 0, 0, 0)
; DI int crow(int i, int h) { return (i & 3) + 8 * (i >> 2) + 4 * h; }
; DI void hgrn_out(const Params& P, int l, int item, char* smem) {
;     ...
;     _Pragma("unroll") for (int st = 0; st < 2; ++st) {
;       _Pragma("unroll") for (int i = 0; i < 16; ++i) {
;         const int s_ = 32 * st + crow(i, h);
;         const bool ok = dir ? (s_ >= t) : (s_ <= t);
;         sc[st][i] = ok ? sc[st][i] : 0.f;
;       }
;     }
;     _Pragma("unroll") for (int st = 0; st < 2; ++st) {
;       _Pragma("unroll") for (int s2 = 0; s2 < 2; ++s2) {
;         bf16x8 pb = pack8(sc[st][8 * s2], sc[st][8 * s2 + 1], sc[st][8 * s2 + 2], sc[st][8 * s2 + 3],
;                           sc[st][8 * s2 + 4], sc[st][8 * s2 + 5], sc[st][8 * s2 + 6], sc[st][8 * s2 + 7]);
;         _Pragma("unroll") for (int mi = 0; mi < 2; ++mi) {
;           const int dv = 32 * (2 * dh + mi) + r;
;           const bf16_t* vp = P.hvt + (size_t)(head * 128 + dv) * TH + t0 + 32 * st + 16 * s2 + 4 * h;
;           s16x4 lo = *(const s16x4*)vp;
;           s16x4 hi = *(const s16x4*)(vp + 8);
;           bf16x8 va = __builtin_shufflevector(lo, hi, 0, 1, 2, 3, 4, 5, 6, 7);
;           o[mi] = MFMA32(va, pb, o[mi]);
;         }
	v_cmp_eq_u32_e32 vcc, 1, v64
	s_nop 0
	v_cndmask_b32_e64 v64, 0, 1, s[4:5]
	v_readlane_b32 s4, v247, 58
	v_readlane_b32 s5, v247, 59
	v_cndmask_b32_e32 v58, 0, v58, vcc
	s_nop 0
	v_cndmask_b32_e64 v65, 0, 1, s[4:5]
	v_cndmask_b32_e64 v64, v65, v64, s[74:75]
	v_readlane_b32 s4, v246, 2
	v_and_b32_e32 v64, 1, v64
	v_readlane_b32 s5, v246, 3
	v_cmp_eq_u32_e32 vcc, 1, v64
	s_nop 0
	v_cndmask_b32_e64 v64, 0, 1, s[4:5]
	v_readlane_b32 s4, v247, 62
	v_readlane_b32 s5, v247, 63
	v_cndmask_b32_e32 v59, 0, v59, vcc
	s_nop 0
	v_cndmask_b32_e64 v65, 0, 1, s[4:5]
	v_cndmask_b32_e64 v64, v65, v64, s[74:75]
	v_readlane_b32 s4, v246, 6
	v_and_b32_e32 v64, 1, v64
	v_readlane_b32 s5, v246, 7
	v_cmp_eq_u32_e32 vcc, 1, v64
	s_nop 0
	v_cndmask_b32_e64 v64, 0, 1, s[4:5]
	v_readlane_b32 s4, v246, 4
	v_readlane_b32 s5, v246, 5
	v_cndmask_b32_e32 v60, 0, v60, vcc
	s_nop 0
	v_cndmask_b32_e64 v65, 0, 1, s[4:5]
	v_cndmask_b32_e64 v64, v65, v64, s[74:75]
	v_readlane_b32 s4, v246, 10
	v_and_b32_e32 v64, 1, v64
	v_readlane_b32 s5, v246, 11
	v_cmp_eq_u32_e32 vcc, 1, v64
	s_nop 0
	v_cndmask_b32_e64 v64, 0, 1, s[4:5]
	v_readlane_b32 s4, v246, 8
	v_readlane_b32 s5, v246, 9
	v_cndmask_b32_e32 v61, 0, v61, vcc
	s_nop 0
	v_cndmask_b32_e64 v65, 0, 1, s[4:5]
	v_cndmask_b32_e64 v64, v65, v64, s[74:75]
	v_readlane_b32 s4, v246, 12
	v_and_b32_e32 v64, 1, v64
	v_readlane_b32 s5, v246, 13
	v_cmp_eq_u32_e32 vcc, 1, v64
	v_cndmask_b32_e64 v64, 0, 1, s[84:85]
	v_cndmask_b32_e64 v65, 0, 1, s[4:5]
	v_cndmask_b32_e64 v64, v65, v64, s[74:75]
	v_and_b32_e32 v64, 1, v64
	v_cndmask_b32_e32 v62, 0, v62, vcc
	v_cmp_eq_u32_e32 vcc, 1, v64
	v_cndmask_b32_e64 v64, 0, 1, s[88:89]
	v_cndmask_b32_e64 v65, 0, 1, s[86:87]
	v_cndmask_b32_e64 v64, v65, v64, s[74:75]
	v_and_b32_e32 v64, 1, v64
	v_cndmask_b32_e32 v63, 0, v63, vcc
	v_cmp_eq_u32_e32 vcc, 1, v64
	v_cndmask_b32_e64 v65, 0, 1, s[90:91]
	s_nop 0
	v_cndmask_b32_e32 v64, 0, v32, vcc
	v_cndmask_b32_e64 v32, 0, 1, s[92:93]
	v_cndmask_b32_e64 v32, v65, v32, s[74:75]
	v_and_b32_e32 v32, 1, v32
	v_cmp_eq_u32_e32 vcc, 1, v32
	v_cndmask_b32_e64 v32, 0, 1, s[96:97]
	s_nop 0
	v_cndmask_b32_e32 v65, 0, v33, vcc
	v_cndmask_b32_e64 v33, 0, 1, s[94:95]
	v_cndmask_b32_e64 v32, v33, v32, s[74:75]
	v_and_b32_e32 v32, 1, v32
	v_cmp_eq_u32_e32 vcc, 1, v32
	v_cndmask_b32_e64 v32, 0, 1, s[20:21]
	v_cndmask_b32_e64 v33, 0, 1, s[2:3]
	v_cndmask_b32_e64 v32, v33, v32, s[74:75]
	v_and_b32_e32 v32, 1, v32
	v_cndmask_b32_e32 v66, 0, v34, vcc
	v_cmp_eq_u32_e32 vcc, 1, v32
	v_cndmask_b32_e64 v32, 0, 1, s[24:25]
	v_cndmask_b32_e64 v33, 0, 1, s[22:23]
	v_cndmask_b32_e64 v32, v33, v32, s[74:75]
	v_and_b32_e32 v32, 1, v32
	v_cndmask_b32_e32 v67, 0, v35, vcc
	v_cmp_eq_u32_e32 vcc, 1, v32
	v_cndmask_b32_e64 v32, 0, 1, s[28:29]
	v_cndmask_b32_e64 v33, 0, 1, s[26:27]
	v_cndmask_b32_e64 v32, v33, v32, s[74:75]
	v_and_b32_e32 v32, 1, v32
	v_cndmask_b32_e32 v68, 0, v36, vcc
	v_cmp_eq_u32_e32 vcc, 1, v32
	v_cndmask_b32_e64 v32, 0, 1, s[34:35]
	v_cndmask_b32_e64 v33, 0, 1, s[30:31]
	v_cndmask_b32_e64 v32, v33, v32, s[74:75]
	v_and_b32_e32 v32, 1, v32
	v_cndmask_b32_e32 v69, 0, v37, vcc
	v_cmp_eq_u32_e32 vcc, 1, v32
	v_cndmask_b32_e64 v32, 0, 1, s[0:1]
	v_cndmask_b32_e64 v33, 0, 1, s[36:37]
	v_cndmask_b32_e64 v32, v33, v32, s[74:75]
	v_and_b32_e32 v32, 1, v32
	v_cndmask_b32_e32 v70, 0, v38, vcc
	v_cmp_eq_u32_e32 vcc, 1, v32
	v_cndmask_b32_e64 v32, 0, 1, s[40:41]
	v_cndmask_b32_e64 v33, 0, 1, s[38:39]
	v_cndmask_b32_e64 v32, v33, v32, s[74:75]
	v_and_b32_e32 v32, 1, v32
	v_cndmask_b32_e32 v71, 0, v39, vcc
	v_cmp_eq_u32_e32 vcc, 1, v32
	v_cndmask_b32_e64 v32, 0, 1, s[44:45]
	v_cndmask_b32_e64 v33, 0, 1, s[42:43]
	v_cndmask_b32_e64 v32, v33, v32, s[74:75]
	v_and_b32_e32 v32, 1, v32
	v_cndmask_b32_e32 v72, 0, v40, vcc
	v_cmp_eq_u32_e32 vcc, 1, v32
	v_cndmask_b32_e64 v32, 0, 1, s[48:49]
	v_cndmask_b32_e64 v33, 0, 1, s[46:47]
	v_cndmask_b32_e64 v32, v33, v32, s[74:75]
	v_and_b32_e32 v32, 1, v32
	v_cndmask_b32_e32 v73, 0, v41, vcc
	v_cmp_eq_u32_e32 vcc, 1, v32
	v_cndmask_b32_e64 v32, 0, 1, s[52:53]
	v_cndmask_b32_e64 v33, 0, 1, s[50:51]
	v_cndmask_b32_e64 v32, v33, v32, s[74:75]
	v_and_b32_e32 v32, 1, v32
	v_cndmask_b32_e32 v74, 0, v42, vcc
	v_cmp_eq_u32_e32 vcc, 1, v32
	v_cndmask_b32_e64 v32, 0, 1, s[56:57]
	v_cndmask_b32_e64 v33, 0, 1, s[54:55]
	v_cndmask_b32_e64 v32, v33, v32, s[74:75]
	v_and_b32_e32 v32, 1, v32
	v_cndmask_b32_e32 v75, 0, v43, vcc
	v_cmp_eq_u32_e32 vcc, 1, v32
	v_cndmask_b32_e64 v32, 0, 1, s[60:61]
	v_cndmask_b32_e64 v33, 0, 1, s[58:59]
	v_cndmask_b32_e64 v32, v33, v32, s[74:75]
	v_and_b32_e32 v32, 1, v32
	v_cndmask_b32_e32 v44, 0, v44, vcc
	v_cmp_eq_u32_e32 vcc, 1, v32
	v_cndmask_b32_e64 v32, 0, 1, s[64:65]
	v_cndmask_b32_e64 v33, 0, 1, s[62:63]
	v_cndmask_b32_e64 v32, v33, v32, s[74:75]
	v_and_b32_e32 v32, 1, v32
	v_cndmask_b32_e32 v45, 0, v45, vcc
	v_cmp_eq_u32_e32 vcc, 1, v32
	v_cndmask_b32_e64 v32, 0, 1, s[68:69]
	v_cndmask_b32_e64 v33, 0, 1, s[66:67]
	v_cndmask_b32_e64 v32, v33, v32, s[74:75]
	v_and_b32_e32 v32, 1, v32
	v_cndmask_b32_e32 v46, 0, v46, vcc
	v_cmp_eq_u32_e32 vcc, 1, v32
	global_load_dwordx2 v[32:33], v[86:87], off
	global_load_dwordx2 v[34:35], v[86:87], off offset:16
	global_load_dwordx2 v[36:37], v[88:89], off
	v_cvt_pk_bf16_f32 v40, v48, v49
	v_cvt_pk_bf16_f32 v41, v50, v51
	v_cvt_pk_bf16_f32 v42, v52, v53
	v_cvt_pk_bf16_f32 v43, v54, v55
	v_cndmask_b32_e32 v47, 0, v47, vcc
	s_and_b64 vcc, exec, s[70:71]
	s_waitcnt vmcnt(1)
; #define MFMA32(a, b, c) __builtin_amdgcn_mfma_f32_32x32x16_bf16((a), (b), (c), 0, 0, 0)
; DI void hgrn_out(const Params& P, int l, int item, char* smem) {
;     ...
;     _Pragma("unroll") for (int st = 0; st < 2; ++st) {
;       _Pragma("unroll") for (int s2 = 0; s2 < 2; ++s2) {
;         bf16x8 pb = pack8(sc[st][8 * s2], sc[st][8 * s2 + 1], sc[st][8 * s2 + 2], sc[st][8 * s2 + 3],
;                           sc[st][8 * s2 + 4], sc[st][8 * s2 + 5], sc[st][8 * s2 + 6], sc[st][8 * s2 + 7]);
;         _Pragma("unroll") for (int mi = 0; mi < 2; ++mi) {
;           const int dv = 32 * (2 * dh + mi) + r;
;           const bf16_t* vp = P.hvt + (size_t)(head * 128 + dv) * TH + t0 + 32 * st + 16 * s2 + 4 * h;
;           s16x4 lo = *(const s16x4*)vp;
;           s16x4 hi = *(const s16x4*)(vp + 8);
;           bf16x8 va = __builtin_shufflevector(lo, hi, 0, 1, 2, 3, 4, 5, 6, 7);
;           o[mi] = MFMA32(va, pb, o[mi]);
;         }
;       }
;     }
;   }
;   float sq = 0.f;
;   _Pragma("unroll") for (int mi = 0; mi < 2; ++mi) {
;     _Pragma("unroll") for (int i = 0; i < 16; ++i) sq += o[mi][i] * o[mi][i];
;   }
;   sq += __shfl_xor(sq, 32);
;   if (h == 0) ssq[dh * 64 + t] = sq;
	v_mfma_f32_32x32x16_bf16 v[16:31], v[32:35], v[40:43], v[16:31]
	global_load_dwordx2 v[38:39], v[88:89], off offset:16
	global_load_dwordx2 v[32:33], v[86:87], off offset:32
	s_mov_b64 s[74:75], 0
	s_waitcnt vmcnt(1)
	v_mfma_f32_32x32x16_bf16 v[0:15], v[36:39], v[40:43], v[0:15]
	global_load_dwordx2 v[34:35], v[86:87], off offset:48
	global_load_dwordx2 v[36:37], v[90:91], off
	v_cvt_pk_bf16_f32 v40, v56, v57
	v_cvt_pk_bf16_f32 v41, v58, v59
	v_cvt_pk_bf16_f32 v42, v60, v61
	v_cvt_pk_bf16_f32 v43, v62, v63
	s_waitcnt vmcnt(1)
	s_nop 0
	v_mfma_f32_32x32x16_bf16 v[16:31], v[32:35], v[40:43], v[16:31]
	global_load_dwordx2 v[38:39], v[90:91], off offset:16
	global_load_dwordx2 v[32:33], v[86:87], off offset:64
	s_waitcnt vmcnt(1)
	v_mfma_f32_32x32x16_bf16 v[0:15], v[36:39], v[40:43], v[0:15]
	global_load_dwordx2 v[34:35], v[86:87], off offset:80
	global_load_dwordx2 v[36:37], v[92:93], off
	v_cvt_pk_bf16_f32 v40, v64, v65
	v_cvt_pk_bf16_f32 v41, v66, v67
	v_cvt_pk_bf16_f32 v42, v68, v69
	v_cvt_pk_bf16_f32 v43, v70, v71
	s_waitcnt vmcnt(1)
	s_nop 0
	v_mfma_f32_32x32x16_bf16 v[16:31], v[32:35], v[40:43], v[16:31]
	global_load_dwordx2 v[38:39], v[92:93], off offset:16
	global_load_dwordx2 v[32:33], v[86:87], off offset:96
	s_waitcnt vmcnt(1)
	v_mfma_f32_32x32x16_bf16 v[0:15], v[36:39], v[40:43], v[0:15]
	global_load_dwordx2 v[34:35], v[86:87], off offset:112
	global_load_dwordx2 v[36:37], v[94:95], off
	global_load_dwordx2 v[38:39], v[94:95], off offset:16
	v_cvt_pk_bf16_f32 v40, v72, v73
	v_cvt_pk_bf16_f32 v41, v74, v75
	v_cvt_pk_bf16_f32 v42, v44, v45
	v_cvt_pk_bf16_f32 v43, v46, v47
	s_waitcnt vmcnt(2)
	s_nop 0
	v_mfma_f32_32x32x16_bf16 v[16:31], v[32:35], v[40:43], v[16:31]
	s_waitcnt vmcnt(0)
	v_mfma_f32_32x32x16_bf16 v[0:15], v[36:39], v[40:43], v[0:15]
	s_cbranch_vccz .LBB0_735
	s_nop 8
	v_mul_f32_e32 v32, v17, v17
	v_fmac_f32_e32 v32, v16, v16
	v_fmac_f32_e32 v32, v18, v18
	v_fmac_f32_e32 v32, v19, v19
	v_fmac_f32_e32 v32, v20, v20
	v_fmac_f32_e32 v32, v21, v21
	v_fmac_f32_e32 v32, v22, v22
	v_fmac_f32_e32 v32, v23, v23
	v_fmac_f32_e32 v32, v24, v24
	v_fmac_f32_e32 v32, v25, v25
	v_fmac_f32_e32 v32, v26, v26
	v_fmac_f32_e32 v32, v27, v27
	v_fmac_f32_e32 v32, v28, v28
	v_fmac_f32_e32 v32, v29, v29
	v_fmac_f32_e32 v32, v30, v30
	v_fmac_f32_e32 v32, v31, v31
	v_fmac_f32_e32 v32, v0, v0
	v_fmac_f32_e32 v32, v1, v1
	v_fmac_f32_e32 v32, v2, v2
	v_fmac_f32_e32 v32, v3, v3
	v_fmac_f32_e32 v32, v4, v4
	v_fmac_f32_e32 v32, v5, v5
	v_fmac_f32_e32 v32, v6, v6
	v_fmac_f32_e32 v32, v7, v7
	v_fmac_f32_e32 v32, v8, v8
	v_fmac_f32_e32 v32, v9, v9
	v_fmac_f32_e32 v32, v10, v10
	v_fmac_f32_e32 v32, v11, v11
	v_fmac_f32_e32 v32, v12, v12
	v_fmac_f32_e32 v32, v13, v13
	v_cmp_lt_i32_e32 vcc, v199, v198
	v_fmac_f32_e32 v32, v14, v14
	v_fmac_f32_e32 v32, v15, v15
	v_cndmask_b32_e32 v33, v145, v199, vcc
	v_lshlrev_b32_e32 v33, 2, v33
	ds_bpermute_b32 v33, v33, v32
	v_cmp_eq_u32_e32 vcc, 0, v136
	s_and_saveexec_b64 s[0:1], vcc
	v_readlane_b32 s52, v250, 46
	s_cbranch_execz .LBB0_733
	s_waitcnt lgkmcnt(0)
	v_add_f32_e32 v32, v32, v33
	v_lshlrev_b32_e32 v33, 2, v135
	v_lshlrev_b32_e32 v34, 2, v109
	v_add3_u32 v33, s52, v33, v34
	ds_write_b32 v33, v32 offset:34816
	s_branch .LBB0_733
